# merge GEMM epilogue: hoist 32 PROJ loads to epilogue top, counted vmcnt waits
# speedup vs baseline: 1.0087x; 1.0087x over previous
.LBB0_1606:
	v_lshl_add_u32 v142, s52, 8, v146
	v_lshl_or_b32 v140, s26, 6, v148
	v_ashrrev_i32_e32 v143, 31, v142
	v_ashrrev_i32_e32 v141, 31, v140
	v_lshlrev_b64 v[144:145], 13, v[142:143]
	v_lshl_add_u64 v[144:145], s[6:7], 0, v[144:145]
	v_lshlrev_b64 v[140:141], 1, v[140:141]
	v_lshl_add_u64 v[144:145], v[144:145], 0, v[140:141]
	global_load_dwordx2 v[160:161], v[144:145], off
	global_load_dwordx2 v[162:163], v[144:145], off offset:2048
	v_add_co_u32_e32 v220, vcc, 0x1000, v144
	s_nop 1
	v_addc_co_u32_e32 v221, vcc, 0, v145, vcc
	global_load_dwordx2 v[164:165], v[220:221], off
	global_load_dwordx2 v[166:167], v[220:221], off offset:2048
	v_add_co_u32_e32 v224, vcc, 0x20000, v144
	s_nop 1
	v_addc_co_u32_e32 v225, vcc, 0, v145, vcc
	global_load_dwordx2 v[168:169], v[224:225], off
	global_load_dwordx2 v[170:171], v[224:225], off offset:2048
	v_add_co_u32_e32 v226, vcc, 0x21000, v144
	s_nop 1
	v_addc_co_u32_e32 v227, vcc, 0, v145, vcc
	global_load_dwordx2 v[172:173], v[226:227], off
	global_load_dwordx2 v[174:175], v[226:227], off offset:2048
	v_add_co_u32_e32 v242, vcc, 0x40000, v144
	s_nop 1
	v_addc_co_u32_e32 v243, vcc, 0, v145, vcc
	global_load_dwordx2 v[176:177], v[242:243], off
	global_load_dwordx2 v[178:179], v[242:243], off offset:2048
	v_add_co_u32_e32 v244, vcc, 0x41000, v144
	s_nop 1
	v_addc_co_u32_e32 v245, vcc, 0, v145, vcc
	global_load_dwordx2 v[180:181], v[244:245], off
	global_load_dwordx2 v[182:183], v[244:245], off offset:2048
	v_add_co_u32_e32 v246, vcc, 0x60000, v144
	s_nop 1
	v_addc_co_u32_e32 v247, vcc, 0, v145, vcc
	global_load_dwordx2 v[184:185], v[246:247], off
	global_load_dwordx2 v[186:187], v[246:247], off offset:2048
	v_add_co_u32_e32 v248, vcc, 0x61000, v144
	s_nop 1
	v_addc_co_u32_e32 v249, vcc, 0, v145, vcc
	global_load_dwordx2 v[188:189], v[248:249], off
	global_load_dwordx2 v[190:191], v[248:249], off offset:2048
	v_add_co_u32_e32 v250, vcc, 0x100000, v144
	s_nop 1
	v_addc_co_u32_e32 v251, vcc, 0, v145, vcc
	global_load_dwordx2 v[192:193], v[250:251], off
	global_load_dwordx2 v[194:195], v[250:251], off offset:2048
	v_add_co_u32_e32 v252, vcc, 0x101000, v144
	s_nop 1
	v_addc_co_u32_e32 v253, vcc, 0, v145, vcc
	global_load_dwordx2 v[196:197], v[252:253], off
	global_load_dwordx2 v[198:199], v[252:253], off offset:2048
	v_add_co_u32_e32 v210, vcc, 0x120000, v144
	s_nop 1
	v_addc_co_u32_e32 v211, vcc, 0, v145, vcc
	global_load_dwordx2 v[200:201], v[210:211], off
	global_load_dwordx2 v[202:203], v[210:211], off offset:2048
	v_add_co_u32_e32 v220, vcc, 0x121000, v144
	s_nop 1
	v_addc_co_u32_e32 v221, vcc, 0, v145, vcc
	global_load_dwordx2 v[204:205], v[220:221], off
	global_load_dwordx2 v[206:207], v[220:221], off offset:2048
	v_add_co_u32_e32 v224, vcc, 0x140000, v144
	s_nop 1
	v_addc_co_u32_e32 v225, vcc, 0, v145, vcc
	global_load_dwordx2 v[208:209], v[224:225], off
	global_load_dwordx2 v[228:229], v[224:225], off offset:2048
	v_add_co_u32_e32 v226, vcc, 0x141000, v144
	s_nop 1
	v_addc_co_u32_e32 v227, vcc, 0, v145, vcc
	global_load_dwordx2 v[230:231], v[226:227], off
	global_load_dwordx2 v[232:233], v[226:227], off offset:2048
	v_add_co_u32_e32 v242, vcc, 0x160000, v144
	s_nop 1
	v_addc_co_u32_e32 v243, vcc, 0, v145, vcc
	global_load_dwordx2 v[234:235], v[242:243], off
	global_load_dwordx2 v[236:237], v[242:243], off offset:2048
	v_add_co_u32_e32 v244, vcc, 0x161000, v144
	s_nop 1
	v_addc_co_u32_e32 v245, vcc, 0, v145, vcc
	global_load_dwordx2 v[238:239], v[244:245], off
	global_load_dwordx2 v[240:241], v[244:245], off offset:2048
	s_nop 0
	s_nop 0
	v_mul_f32_e32 v127, 0xbfb8aa3b, v127
	v_exp_f32_e32 v127, v127
	v_mul_f32_e32 v126, 0xbfb8aa3b, v126
	v_mul_f32_e32 v122, 0xbfb8aa3b, v122
	v_exp_f32_e32 v126, v126
	v_add_f32_e32 v127, 1.0, v127
	v_rcp_f32_e32 v150, v127
	v_mul_f32_e32 v127, 0xbfb8aa3b, v128
	v_exp_f32_e32 v127, v127
	v_exp_f32_e32 v122, v122
	v_add_f32_e32 v126, 1.0, v126
	v_rcp_f32_e32 v126, v126
	v_add_f32_e32 v127, 1.0, v127
	v_rcp_f32_e32 v128, v127
	v_mul_f32_e32 v127, 0xbfb8aa3b, v129
	v_exp_f32_e32 v127, v127
	v_add_f32_e32 v122, 1.0, v122
	v_mul_f32_e32 v118, 0xbfb8aa3b, v118
	v_mul_f32_e32 v114, 0xbfb8aa3b, v114
	v_add_f32_e32 v127, 1.0, v127
	v_rcp_f32_e32 v154, v127
	v_rcp_f32_e32 v127, v122
	v_exp_f32_e32 v118, v118
	v_exp_f32_e32 v114, v114
	v_mul_f32_e32 v111, 0xbfb8aa3b, v111
	v_exp_f32_e32 v111, v111
	v_add_f32_e32 v118, 1.0, v118
	v_add_f32_e32 v114, 1.0, v114
	v_mul_f32_e32 v110, 0xbfb8aa3b, v110
	v_add_f32_e32 v111, 1.0, v111
	v_mul_f32_e32 v106, 0xbfb8aa3b, v106
	v_exp_f32_e32 v110, v110
	v_exp_f32_e32 v106, v106
	v_mul_f32_e32 v102, 0xbfb8aa3b, v102
	v_mul_f32_e32 v98, 0xbfb8aa3b, v98
	v_add_f32_e32 v110, 1.0, v110
	v_add_f32_e32 v106, 1.0, v106
	v_rcp_f32_e32 v110, v110
	v_exp_f32_e32 v102, v102
	v_exp_f32_e32 v98, v98
	v_mul_f32_e32 v95, 0xbfb8aa3b, v95
	v_exp_f32_e32 v95, v95
	v_add_f32_e32 v102, 1.0, v102
	v_add_f32_e32 v98, 1.0, v98
	v_mul_f32_e32 v94, 0xbfb8aa3b, v94
	v_add_f32_e32 v95, 1.0, v95
	v_mul_f32_e32 v90, 0xbfb8aa3b, v90
	v_exp_f32_e32 v94, v94
	v_exp_f32_e32 v90, v90
	v_mul_f32_e32 v86, 0xbfb8aa3b, v86
	v_mul_f32_e32 v82, 0xbfb8aa3b, v82
	v_add_f32_e32 v94, 1.0, v94
	v_add_f32_e32 v90, 1.0, v90
	v_rcp_f32_e32 v94, v94
	v_exp_f32_e32 v86, v86
	v_exp_f32_e32 v82, v82
	v_mul_f32_e32 v79, 0xbfb8aa3b, v79
	v_exp_f32_e32 v79, v79
	v_add_f32_e32 v86, 1.0, v86
	v_add_f32_e32 v82, 1.0, v82
	v_mul_f32_e32 v78, 0xbfb8aa3b, v78
	v_add_f32_e32 v79, 1.0, v79
	v_mul_f32_e32 v74, 0xbfb8aa3b, v74
	v_exp_f32_e32 v78, v78
	v_exp_f32_e32 v74, v74
	v_mul_f32_e32 v70, 0xbfb8aa3b, v70
	v_mul_f32_e32 v66, 0xbfb8aa3b, v66
	v_add_f32_e32 v78, 1.0, v78
	v_add_f32_e32 v74, 1.0, v74
	v_rcp_f32_e32 v78, v78
	v_exp_f32_e32 v70, v70
	v_exp_f32_e32 v66, v66
	v_mul_f32_e32 v63, 0xbfb8aa3b, v63
	v_exp_f32_e32 v63, v63
	v_add_f32_e32 v70, 1.0, v70
	v_add_f32_e32 v66, 1.0, v66
	v_mul_f32_e32 v62, 0xbfb8aa3b, v62
	v_add_f32_e32 v63, 1.0, v63
	s_waitcnt vmcnt(30)
	v_lshlrev_b32_e32 v158, 16, v160
	v_lshlrev_b32_e32 v159, 16, v162
	v_pk_mul_f32 v[126:127], v[126:127], v[158:159]
	v_mul_f32_e32 v58, 0xbfb8aa3b, v58
	v_add_f32_e32 v122, 0, v126
	v_add_f32_e32 v127, v122, v127
	v_mul_f32_e32 v122, 0xbfb8aa3b, v123
	v_exp_f32_e32 v122, v122
	v_and_b32_e32 v123, 0xffff0000, v162
	v_exp_f32_e32 v62, v62
	v_exp_f32_e32 v58, v58
	v_add_f32_e32 v122, 1.0, v122
	v_rcp_f32_e32 v151, v122
	v_and_b32_e32 v122, 0xffff0000, v160
	v_add_f32_e32 v62, 1.0, v62
	v_add_f32_e32 v58, 1.0, v58
	v_pk_mul_f32 v[122:123], v[150:151], v[122:123]
	v_rcp_f32_e32 v62, v62
	v_add_f32_e32 v122, 0, v122
	v_add_f32_e32 v152, v122, v123
	v_mul_f32_e32 v122, 0xbfb8aa3b, v124
	v_exp_f32_e32 v122, v122
	v_lshlrev_b32_e32 v123, 16, v163
	v_add_co_u32_e32 v124, vcc, s44, v144
	v_add_f32_e32 v122, 1.0, v122
	v_rcp_f32_e32 v129, v122
	v_lshlrev_b32_e32 v122, 16, v161
	v_mul_f32_e32 v54, 0xbfb8aa3b, v54
	v_mul_f32_e32 v50, 0xbfb8aa3b, v50
	v_pk_mul_f32 v[122:123], v[128:129], v[122:123]
	v_rcp_f32_e32 v128, v118
	v_add_f32_e32 v122, 0, v122
	v_add_f32_e32 v151, v122, v123
	v_mul_f32_e32 v122, 0xbfb8aa3b, v125
	v_exp_f32_e32 v122, v122
	v_and_b32_e32 v123, 0xffff0000, v163
	v_addc_co_u32_e32 v125, vcc, 0, v145, vcc
	v_add_f32_e32 v122, 1.0, v122
	v_rcp_f32_e32 v155, v122
	v_and_b32_e32 v122, 0xffff0000, v161
	v_rcp_f32_e32 v129, v114
	v_mul_f32_e32 v118, 0xbfb8aa3b, v119
	v_pk_mul_f32 v[122:123], v[154:155], v[122:123]
	v_exp_f32_e32 v118, v118
	v_add_f32_e32 v122, 0, v122
	v_add_f32_e32 v150, v122, v123
	s_nop 0
	v_add_f32_e32 v118, 1.0, v118
	s_nop 0
	v_rcp_f32_e32 v126, v118
	v_mul_f32_e32 v118, 0xbfb8aa3b, v120
	v_exp_f32_e32 v118, v118
	v_exp_f32_e32 v54, v54
	v_exp_f32_e32 v50, v50
	v_mul_f32_e32 v47, 0xbfb8aa3b, v47
	v_add_f32_e32 v118, 1.0, v118
	v_rcp_f32_e32 v120, v118
	v_mul_f32_e32 v118, 0xbfb8aa3b, v121
	v_exp_f32_e32 v118, v118
	v_add_f32_e32 v54, 1.0, v54
	v_add_f32_e32 v50, 1.0, v50
	v_exp_f32_e32 v47, v47
	v_add_f32_e32 v118, 1.0, v118
	v_rcp_f32_e32 v118, v118
	v_mul_f32_e32 v46, 0xbfb8aa3b, v46
	v_add_f32_e32 v47, 1.0, v47
	v_mul_f32_e32 v42, 0xbfb8aa3b, v42
	v_exp_f32_e32 v46, v46
	v_exp_f32_e32 v42, v42
	v_mul_f32_e32 v38, 0xbfb8aa3b, v38
	v_mul_f32_e32 v34, 0xbfb8aa3b, v34
	v_add_f32_e32 v46, 1.0, v46
	v_add_f32_e32 v42, 1.0, v42
	v_rcp_f32_e32 v46, v46
	v_exp_f32_e32 v38, v38
	v_exp_f32_e32 v34, v34
	v_mul_f32_e32 v31, 0xbfb8aa3b, v31
	v_exp_f32_e32 v31, v31
	v_add_f32_e32 v38, 1.0, v38
	v_add_f32_e32 v34, 1.0, v34
	v_mul_f32_e32 v30, 0xbfb8aa3b, v30
	v_add_f32_e32 v31, 1.0, v31
	v_mul_f32_e32 v26, 0xbfb8aa3b, v26
	v_exp_f32_e32 v30, v30
	v_exp_f32_e32 v26, v26
	v_mul_f32_e32 v22, 0xbfb8aa3b, v22
	v_mul_f32_e32 v18, 0xbfb8aa3b, v18
	v_add_f32_e32 v30, 1.0, v30
	v_add_f32_e32 v26, 1.0, v26
	v_rcp_f32_e32 v30, v30
	v_exp_f32_e32 v22, v22
	v_exp_f32_e32 v18, v18
	v_mul_f32_e32 v15, 0xbfb8aa3b, v15
	v_exp_f32_e32 v15, v15
	v_add_f32_e32 v22, 1.0, v22
	v_add_f32_e32 v18, 1.0, v18
	v_mul_f32_e32 v14, 0xbfb8aa3b, v14
	v_add_f32_e32 v15, 1.0, v15
	v_mul_f32_e32 v10, 0xbfb8aa3b, v10
	v_exp_f32_e32 v14, v14
	v_exp_f32_e32 v10, v10
	v_mul_f32_e32 v6, 0xbfb8aa3b, v6
	v_mul_f32_e32 v2, 0xbfb8aa3b, v2
	v_add_f32_e32 v14, 1.0, v14
	v_add_f32_e32 v10, 1.0, v10
	v_rcp_f32_e32 v14, v14
	v_exp_f32_e32 v6, v6
	v_exp_f32_e32 v2, v2
	s_mov_b64 s[26:27], -1
	v_add_f32_e32 v6, 1.0, v6
	v_add_f32_e32 v2, 1.0, v2
	s_waitcnt vmcnt(29)
	v_lshlrev_b32_e32 v144, 16, v164
	s_waitcnt vmcnt(28)
	v_lshlrev_b32_e32 v145, 16, v166
	v_pk_mul_f32 v[128:129], v[128:129], v[144:145]
	s_nop 0
	v_add_f32_e32 v114, v127, v128
	v_add_f32_e32 v128, v114, v129
	v_mul_f32_e32 v114, 0xbfb8aa3b, v115
	v_exp_f32_e32 v114, v114
	v_and_b32_e32 v115, 0xffff0000, v166
	v_add_f32_e32 v114, 1.0, v114
	v_rcp_f32_e32 v127, v114
	v_and_b32_e32 v114, 0xffff0000, v164
	v_pk_mul_f32 v[114:115], v[126:127], v[114:115]
	s_nop 0
	v_add_f32_e32 v114, v152, v114
	v_add_f32_e32 v122, v114, v115
	v_mul_f32_e32 v114, 0xbfb8aa3b, v116
	v_exp_f32_e32 v114, v114
	v_lshlrev_b32_e32 v115, 16, v167
	v_add_f32_e32 v114, 1.0, v114
	v_rcp_f32_e32 v121, v114
	v_lshlrev_b32_e32 v114, 16, v165
	v_pk_mul_f32 v[114:115], v[120:121], v[114:115]
	s_nop 0
	v_add_f32_e32 v114, v151, v114
	v_add_f32_e32 v116, v114, v115
	v_mul_f32_e32 v114, 0xbfb8aa3b, v117
	v_exp_f32_e32 v114, v114
	v_and_b32_e32 v115, 0xffff0000, v167
	v_add_f32_e32 v114, 1.0, v114
	v_rcp_f32_e32 v119, v114
	v_and_b32_e32 v114, 0xffff0000, v165
	v_pk_mul_f32 v[114:115], v[118:119], v[114:115]
	s_nop 0
	v_add_f32_e32 v114, v150, v114
	v_add_f32_e32 v115, v114, v115
	v_cvt_pk_bf16_f32 v114, v128, v122
	v_cvt_pk_bf16_f32 v115, v116, v115
	v_lshlrev_b64 v[116:117], 11, v[142:143]
	v_lshl_add_u64 v[116:117], s[8:9], 0, v[116:117]
	v_lshl_add_u64 v[116:117], v[116:117], 0, v[140:141]
	global_store_dwordx2 v[116:117], v[114:115], off
	v_or_b32_e32 v114, 16, v142
	v_ashrrev_i32_e32 v115, 31, v114
	v_lshlrev_b64 v[116:117], 13, v[114:115]
	v_lshl_add_u64 v[116:117], s[6:7], 0, v[116:117]
	v_lshl_add_u64 v[116:117], v[116:117], 0, v[140:141]
	s_nop 0
	s_nop 0
	v_rcp_f32_e32 v118, v111
	v_mul_f32_e32 v111, 0xbfb8aa3b, v112
	v_exp_f32_e32 v111, v111
	s_waitcnt vmcnt(28)
	v_lshlrev_b32_e32 v126, 16, v168
	v_add_f32_e32 v111, 1.0, v111
	v_rcp_f32_e32 v112, v111
	v_mul_f32_e32 v111, 0xbfb8aa3b, v113
	v_exp_f32_e32 v111, v111
	s_waitcnt vmcnt(27)
	v_lshlrev_b32_e32 v127, 16, v170
	v_add_f32_e32 v111, 1.0, v111
	v_rcp_f32_e32 v122, v111
	v_rcp_f32_e32 v111, v106
	s_nop 0
	v_pk_mul_f32 v[110:111], v[110:111], v[126:127]
	s_nop 0
	v_add_f32_e32 v106, 0, v110
	v_add_f32_e32 v111, v106, v111
	v_mul_f32_e32 v106, 0xbfb8aa3b, v107
	v_exp_f32_e32 v106, v106
	v_and_b32_e32 v107, 0xffff0000, v170
	v_add_f32_e32 v106, 1.0, v106
	v_rcp_f32_e32 v119, v106
	v_and_b32_e32 v106, 0xffff0000, v168
	v_pk_mul_f32 v[106:107], v[118:119], v[106:107]
	s_nop 0
	v_add_f32_e32 v106, 0, v106
	v_add_f32_e32 v120, v106, v107
	v_mul_f32_e32 v106, 0xbfb8aa3b, v108
	v_exp_f32_e32 v106, v106
	v_lshlrev_b32_e32 v107, 16, v171
	v_add_co_u32_e32 v108, vcc, s44, v116
	v_add_f32_e32 v106, 1.0, v106
	v_rcp_f32_e32 v113, v106
	v_lshlrev_b32_e32 v106, 16, v169
	v_pk_mul_f32 v[106:107], v[112:113], v[106:107]
	s_nop 0
	v_add_f32_e32 v106, 0, v106
	v_add_f32_e32 v119, v106, v107
	v_mul_f32_e32 v106, 0xbfb8aa3b, v109
	v_exp_f32_e32 v106, v106
	v_and_b32_e32 v107, 0xffff0000, v171
	v_addc_co_u32_e32 v109, vcc, 0, v117, vcc
	v_add_f32_e32 v106, 1.0, v106
	v_rcp_f32_e32 v123, v106
	v_and_b32_e32 v106, 0xffff0000, v169
	v_rcp_f32_e32 v112, v102
	v_rcp_f32_e32 v113, v98
	v_pk_mul_f32 v[106:107], v[122:123], v[106:107]
	v_mul_f32_e32 v102, 0xbfb8aa3b, v103
	v_add_f32_e32 v106, 0, v106
	v_add_f32_e32 v118, v106, v107
	s_nop 0
	v_exp_f32_e32 v102, v102
	s_nop 0
	v_add_f32_e32 v102, 1.0, v102
	v_rcp_f32_e32 v110, v102
	v_mul_f32_e32 v102, 0xbfb8aa3b, v104
	v_exp_f32_e32 v102, v102
	s_waitcnt vmcnt(26)
	v_lshlrev_b32_e32 v116, 16, v172
	v_add_f32_e32 v102, 1.0, v102
	s_waitcnt vmcnt(25)
	v_lshlrev_b32_e32 v117, 16, v174
	v_pk_mul_f32 v[112:113], v[112:113], v[116:117]
	v_rcp_f32_e32 v104, v102
	v_add_f32_e32 v98, v111, v112
	v_add_f32_e32 v112, v98, v113
	v_mul_f32_e32 v98, 0xbfb8aa3b, v99
	v_exp_f32_e32 v98, v98
	v_and_b32_e32 v99, 0xffff0000, v174
	v_mul_f32_e32 v102, 0xbfb8aa3b, v105
	v_exp_f32_e32 v102, v102
	v_add_f32_e32 v98, 1.0, v98
	v_rcp_f32_e32 v111, v98
	v_and_b32_e32 v98, 0xffff0000, v172
	v_add_f32_e32 v102, 1.0, v102
	v_rcp_f32_e32 v102, v102
	v_pk_mul_f32 v[98:99], v[110:111], v[98:99]
	s_nop 0
	v_add_f32_e32 v98, v120, v98
	v_add_f32_e32 v106, v98, v99
	v_mul_f32_e32 v98, 0xbfb8aa3b, v100
	v_exp_f32_e32 v98, v98
	v_lshlrev_b32_e32 v99, 16, v175
	v_add_f32_e32 v98, 1.0, v98
	v_rcp_f32_e32 v105, v98
	v_lshlrev_b32_e32 v98, 16, v173
	v_pk_mul_f32 v[98:99], v[104:105], v[98:99]
	s_nop 0
	v_add_f32_e32 v98, v119, v98
	v_add_f32_e32 v100, v98, v99
	v_mul_f32_e32 v98, 0xbfb8aa3b, v101
	v_exp_f32_e32 v98, v98
	v_and_b32_e32 v99, 0xffff0000, v175
	v_add_f32_e32 v98, 1.0, v98
	v_rcp_f32_e32 v103, v98
	v_and_b32_e32 v98, 0xffff0000, v173
	v_pk_mul_f32 v[98:99], v[102:103], v[98:99]
	s_nop 0
	v_add_f32_e32 v98, v118, v98
	v_add_f32_e32 v99, v98, v99
	v_cvt_pk_bf16_f32 v98, v112, v106
	v_cvt_pk_bf16_f32 v99, v100, v99
	v_lshlrev_b64 v[100:101], 11, v[114:115]
	v_lshl_add_u64 v[100:101], s[8:9], 0, v[100:101]
	v_lshl_add_u64 v[100:101], v[100:101], 0, v[140:141]
	global_store_dwordx2 v[100:101], v[98:99], off
	v_or_b32_e32 v98, 32, v142
	v_ashrrev_i32_e32 v99, 31, v98
	v_lshlrev_b64 v[100:101], 13, v[98:99]
	v_lshl_add_u64 v[100:101], s[6:7], 0, v[100:101]
	v_lshl_add_u64 v[100:101], v[100:101], 0, v[140:141]
	s_nop 0
	s_nop 0
	v_rcp_f32_e32 v102, v95
	v_mul_f32_e32 v95, 0xbfb8aa3b, v96
	v_exp_f32_e32 v95, v95
	s_waitcnt vmcnt(25)
	v_lshlrev_b32_e32 v110, 16, v176
	v_add_f32_e32 v95, 1.0, v95
	v_rcp_f32_e32 v96, v95
	v_mul_f32_e32 v95, 0xbfb8aa3b, v97
	v_exp_f32_e32 v95, v95
	s_waitcnt vmcnt(24)
	v_lshlrev_b32_e32 v111, 16, v178
	v_add_f32_e32 v95, 1.0, v95
	v_rcp_f32_e32 v106, v95
	v_rcp_f32_e32 v95, v90
	s_nop 0
	v_pk_mul_f32 v[94:95], v[94:95], v[110:111]
	s_nop 0
	v_add_f32_e32 v90, 0, v94
	v_add_f32_e32 v95, v90, v95
	v_mul_f32_e32 v90, 0xbfb8aa3b, v91
	v_exp_f32_e32 v90, v90
	v_and_b32_e32 v91, 0xffff0000, v178
	v_add_f32_e32 v90, 1.0, v90
	v_rcp_f32_e32 v103, v90
	v_and_b32_e32 v90, 0xffff0000, v176
	v_pk_mul_f32 v[90:91], v[102:103], v[90:91]
	s_nop 0
	v_add_f32_e32 v90, 0, v90
	v_add_f32_e32 v104, v90, v91
	v_mul_f32_e32 v90, 0xbfb8aa3b, v92
	v_exp_f32_e32 v90, v90
	v_lshlrev_b32_e32 v91, 16, v179
	v_add_co_u32_e32 v92, vcc, s44, v100
	v_add_f32_e32 v90, 1.0, v90
	v_rcp_f32_e32 v97, v90
	v_lshlrev_b32_e32 v90, 16, v177
	v_pk_mul_f32 v[90:91], v[96:97], v[90:91]
	s_nop 0
	v_add_f32_e32 v90, 0, v90
	v_add_f32_e32 v103, v90, v91
	v_mul_f32_e32 v90, 0xbfb8aa3b, v93
	v_exp_f32_e32 v90, v90
	v_and_b32_e32 v91, 0xffff0000, v179
	v_addc_co_u32_e32 v93, vcc, 0, v101, vcc
	v_add_f32_e32 v90, 1.0, v90
	v_rcp_f32_e32 v107, v90
	v_and_b32_e32 v90, 0xffff0000, v177
	v_rcp_f32_e32 v96, v86
	v_rcp_f32_e32 v97, v82
	v_pk_mul_f32 v[90:91], v[106:107], v[90:91]
	v_mul_f32_e32 v86, 0xbfb8aa3b, v87
	v_add_f32_e32 v90, 0, v90
	v_add_f32_e32 v102, v90, v91
	s_nop 0
	v_exp_f32_e32 v86, v86
	s_nop 0
	v_add_f32_e32 v86, 1.0, v86
	v_rcp_f32_e32 v94, v86
	v_mul_f32_e32 v86, 0xbfb8aa3b, v88
	v_exp_f32_e32 v86, v86
	s_waitcnt vmcnt(23)
	v_lshlrev_b32_e32 v100, 16, v180
	v_add_f32_e32 v86, 1.0, v86
	s_waitcnt vmcnt(22)
	v_lshlrev_b32_e32 v101, 16, v182
	v_pk_mul_f32 v[96:97], v[96:97], v[100:101]
	v_rcp_f32_e32 v88, v86
	v_add_f32_e32 v82, v95, v96
	v_add_f32_e32 v96, v82, v97
	v_mul_f32_e32 v82, 0xbfb8aa3b, v83
	v_exp_f32_e32 v82, v82
	v_and_b32_e32 v83, 0xffff0000, v182
	v_mul_f32_e32 v86, 0xbfb8aa3b, v89
	v_exp_f32_e32 v86, v86
	v_add_f32_e32 v82, 1.0, v82
	v_rcp_f32_e32 v95, v82
	v_and_b32_e32 v82, 0xffff0000, v180
	v_add_f32_e32 v86, 1.0, v86
	v_rcp_f32_e32 v86, v86
	v_pk_mul_f32 v[82:83], v[94:95], v[82:83]
	s_nop 0
	v_add_f32_e32 v82, v104, v82
	v_add_f32_e32 v90, v82, v83
	v_mul_f32_e32 v82, 0xbfb8aa3b, v84
	v_exp_f32_e32 v82, v82
	v_lshlrev_b32_e32 v83, 16, v183
	v_add_f32_e32 v82, 1.0, v82
	v_rcp_f32_e32 v89, v82
	v_lshlrev_b32_e32 v82, 16, v181
	v_pk_mul_f32 v[82:83], v[88:89], v[82:83]
	s_nop 0
	v_add_f32_e32 v82, v103, v82
	v_add_f32_e32 v84, v82, v83
	v_mul_f32_e32 v82, 0xbfb8aa3b, v85
	v_exp_f32_e32 v82, v82
	v_and_b32_e32 v83, 0xffff0000, v183
	v_add_f32_e32 v82, 1.0, v82
	v_rcp_f32_e32 v87, v82
	v_and_b32_e32 v82, 0xffff0000, v181
	v_pk_mul_f32 v[82:83], v[86:87], v[82:83]
	s_nop 0
	v_add_f32_e32 v82, v102, v82
	v_add_f32_e32 v83, v82, v83
	v_cvt_pk_bf16_f32 v82, v96, v90
	v_cvt_pk_bf16_f32 v83, v84, v83
	v_lshlrev_b64 v[84:85], 11, v[98:99]
	v_lshl_add_u64 v[84:85], s[8:9], 0, v[84:85]
	v_lshl_add_u64 v[84:85], v[84:85], 0, v[140:141]
	global_store_dwordx2 v[84:85], v[82:83], off
	v_or_b32_e32 v82, 48, v142
	v_ashrrev_i32_e32 v83, 31, v82
	v_lshlrev_b64 v[84:85], 13, v[82:83]
	v_lshl_add_u64 v[84:85], s[6:7], 0, v[84:85]
	v_lshl_add_u64 v[84:85], v[84:85], 0, v[140:141]
	s_nop 0
	s_nop 0
	v_rcp_f32_e32 v86, v79
	v_mul_f32_e32 v79, 0xbfb8aa3b, v80
	v_exp_f32_e32 v79, v79
	s_waitcnt vmcnt(22)
	v_lshlrev_b32_e32 v94, 16, v184
	v_add_f32_e32 v79, 1.0, v79
	v_rcp_f32_e32 v80, v79
	v_mul_f32_e32 v79, 0xbfb8aa3b, v81
	v_exp_f32_e32 v79, v79
	s_waitcnt vmcnt(21)
	v_lshlrev_b32_e32 v95, 16, v186
	v_add_f32_e32 v79, 1.0, v79
	v_rcp_f32_e32 v90, v79
	v_rcp_f32_e32 v79, v74
	s_nop 0
	v_pk_mul_f32 v[78:79], v[78:79], v[94:95]
	s_nop 0
	v_add_f32_e32 v74, 0, v78
	v_add_f32_e32 v79, v74, v79
	v_mul_f32_e32 v74, 0xbfb8aa3b, v75
	v_exp_f32_e32 v74, v74
	v_and_b32_e32 v75, 0xffff0000, v186
	v_add_f32_e32 v74, 1.0, v74
	v_rcp_f32_e32 v87, v74
	v_and_b32_e32 v74, 0xffff0000, v184
	v_pk_mul_f32 v[74:75], v[86:87], v[74:75]
	s_nop 0
	v_add_f32_e32 v74, 0, v74
	v_add_f32_e32 v88, v74, v75
	v_mul_f32_e32 v74, 0xbfb8aa3b, v76
	v_exp_f32_e32 v74, v74
	v_lshlrev_b32_e32 v75, 16, v187
	v_add_co_u32_e32 v76, vcc, s44, v84
	v_add_f32_e32 v74, 1.0, v74
	v_rcp_f32_e32 v81, v74
	v_lshlrev_b32_e32 v74, 16, v185
	v_pk_mul_f32 v[74:75], v[80:81], v[74:75]
	s_nop 0
	v_add_f32_e32 v74, 0, v74
	v_add_f32_e32 v87, v74, v75
	v_mul_f32_e32 v74, 0xbfb8aa3b, v77
	v_exp_f32_e32 v74, v74
	v_and_b32_e32 v75, 0xffff0000, v187
	v_addc_co_u32_e32 v77, vcc, 0, v85, vcc
	v_add_f32_e32 v74, 1.0, v74
	v_rcp_f32_e32 v91, v74
	v_and_b32_e32 v74, 0xffff0000, v185
	v_rcp_f32_e32 v80, v70
	v_rcp_f32_e32 v81, v66
	v_pk_mul_f32 v[74:75], v[90:91], v[74:75]
	v_mul_f32_e32 v70, 0xbfb8aa3b, v71
	v_add_f32_e32 v74, 0, v74
	v_add_f32_e32 v86, v74, v75
	s_nop 0
	v_exp_f32_e32 v70, v70
	s_nop 0
	v_add_f32_e32 v70, 1.0, v70
	v_rcp_f32_e32 v78, v70
	v_mul_f32_e32 v70, 0xbfb8aa3b, v72
	v_exp_f32_e32 v70, v70
	s_waitcnt vmcnt(20)
	v_lshlrev_b32_e32 v84, 16, v188
	v_add_f32_e32 v70, 1.0, v70
	s_waitcnt vmcnt(19)
	v_lshlrev_b32_e32 v85, 16, v190
	v_pk_mul_f32 v[80:81], v[80:81], v[84:85]
	v_rcp_f32_e32 v72, v70
	v_add_f32_e32 v66, v79, v80
	v_add_f32_e32 v80, v66, v81
	v_mul_f32_e32 v66, 0xbfb8aa3b, v67
	v_exp_f32_e32 v66, v66
	v_and_b32_e32 v67, 0xffff0000, v190
	v_mul_f32_e32 v70, 0xbfb8aa3b, v73
	v_exp_f32_e32 v70, v70
	v_add_f32_e32 v66, 1.0, v66
	v_rcp_f32_e32 v79, v66
	v_and_b32_e32 v66, 0xffff0000, v188
	v_add_f32_e32 v70, 1.0, v70
	v_rcp_f32_e32 v70, v70
	v_pk_mul_f32 v[66:67], v[78:79], v[66:67]
	s_nop 0
	v_add_f32_e32 v66, v88, v66
	v_add_f32_e32 v74, v66, v67
	v_mul_f32_e32 v66, 0xbfb8aa3b, v68
	v_exp_f32_e32 v66, v66
	v_lshlrev_b32_e32 v67, 16, v191
	v_add_f32_e32 v66, 1.0, v66
	v_rcp_f32_e32 v73, v66
	v_lshlrev_b32_e32 v66, 16, v189
	v_pk_mul_f32 v[66:67], v[72:73], v[66:67]
	s_nop 0
	v_add_f32_e32 v66, v87, v66
	v_add_f32_e32 v68, v66, v67
	v_mul_f32_e32 v66, 0xbfb8aa3b, v69
	v_exp_f32_e32 v66, v66
	v_and_b32_e32 v67, 0xffff0000, v191
	v_add_f32_e32 v66, 1.0, v66
	v_rcp_f32_e32 v71, v66
	v_and_b32_e32 v66, 0xffff0000, v189
	v_pk_mul_f32 v[66:67], v[70:71], v[66:67]
	s_nop 0
	v_add_f32_e32 v66, v86, v66
	v_add_f32_e32 v67, v66, v67
	v_cvt_pk_bf16_f32 v66, v80, v74
	v_cvt_pk_bf16_f32 v67, v68, v67
	v_lshlrev_b64 v[68:69], 11, v[82:83]
	v_lshl_add_u64 v[68:69], s[8:9], 0, v[68:69]
	v_lshl_add_u64 v[68:69], v[68:69], 0, v[140:141]
	global_store_dwordx2 v[68:69], v[66:67], off
	v_add_u32_e32 v66, 0x80, v142
	v_ashrrev_i32_e32 v67, 31, v66
	v_lshlrev_b64 v[68:69], 13, v[66:67]
	v_lshl_add_u64 v[68:69], s[6:7], 0, v[68:69]
	v_lshl_add_u64 v[68:69], v[68:69], 0, v[140:141]
	s_nop 0
	s_nop 0
	v_rcp_f32_e32 v70, v63
	v_mul_f32_e32 v63, 0xbfb8aa3b, v64
	v_exp_f32_e32 v63, v63
	s_waitcnt vmcnt(19)
	v_lshlrev_b32_e32 v78, 16, v192
	v_add_f32_e32 v63, 1.0, v63
	v_rcp_f32_e32 v64, v63
	v_mul_f32_e32 v63, 0xbfb8aa3b, v65
	v_exp_f32_e32 v63, v63
	s_waitcnt vmcnt(18)
	v_lshlrev_b32_e32 v79, 16, v194
	v_add_f32_e32 v63, 1.0, v63
	v_rcp_f32_e32 v74, v63
	v_rcp_f32_e32 v63, v58
	s_nop 0
	v_pk_mul_f32 v[62:63], v[62:63], v[78:79]
	s_nop 0
	v_add_f32_e32 v58, 0, v62
	v_add_f32_e32 v63, v58, v63
	v_mul_f32_e32 v58, 0xbfb8aa3b, v59
	v_exp_f32_e32 v58, v58
	v_and_b32_e32 v59, 0xffff0000, v194
	v_add_f32_e32 v58, 1.0, v58
	v_rcp_f32_e32 v71, v58
	v_and_b32_e32 v58, 0xffff0000, v192
	v_pk_mul_f32 v[58:59], v[70:71], v[58:59]
	s_nop 0
	v_add_f32_e32 v58, 0, v58
	v_add_f32_e32 v72, v58, v59
	v_mul_f32_e32 v58, 0xbfb8aa3b, v60
	v_exp_f32_e32 v58, v58
	v_lshlrev_b32_e32 v59, 16, v195
	v_add_co_u32_e32 v60, vcc, s44, v68
	v_add_f32_e32 v58, 1.0, v58
	v_rcp_f32_e32 v65, v58
	v_lshlrev_b32_e32 v58, 16, v193
	v_pk_mul_f32 v[58:59], v[64:65], v[58:59]
	s_nop 0
	v_add_f32_e32 v58, 0, v58
	v_add_f32_e32 v71, v58, v59
	v_mul_f32_e32 v58, 0xbfb8aa3b, v61
	v_exp_f32_e32 v58, v58
	v_and_b32_e32 v59, 0xffff0000, v195
	v_addc_co_u32_e32 v61, vcc, 0, v69, vcc
	v_add_f32_e32 v58, 1.0, v58
	v_rcp_f32_e32 v75, v58
	v_and_b32_e32 v58, 0xffff0000, v193
	v_rcp_f32_e32 v64, v54
	v_rcp_f32_e32 v65, v50
	v_pk_mul_f32 v[58:59], v[74:75], v[58:59]
	v_mul_f32_e32 v54, 0xbfb8aa3b, v55
	v_add_f32_e32 v58, 0, v58
	v_add_f32_e32 v70, v58, v59
	s_nop 0
	v_exp_f32_e32 v54, v54
	s_nop 0
	v_add_f32_e32 v54, 1.0, v54
	v_rcp_f32_e32 v62, v54
	v_mul_f32_e32 v54, 0xbfb8aa3b, v56
	v_exp_f32_e32 v54, v54
	s_waitcnt vmcnt(17)
	v_lshlrev_b32_e32 v68, 16, v196
	v_add_f32_e32 v54, 1.0, v54
	s_waitcnt vmcnt(16)
	v_lshlrev_b32_e32 v69, 16, v198
	v_pk_mul_f32 v[64:65], v[64:65], v[68:69]
	v_rcp_f32_e32 v56, v54
	v_add_f32_e32 v50, v63, v64
	v_add_f32_e32 v64, v50, v65
	v_mul_f32_e32 v50, 0xbfb8aa3b, v51
	v_exp_f32_e32 v50, v50
	v_and_b32_e32 v51, 0xffff0000, v198
	v_mul_f32_e32 v54, 0xbfb8aa3b, v57
	v_exp_f32_e32 v54, v54
	v_add_f32_e32 v50, 1.0, v50
	v_rcp_f32_e32 v63, v50
	v_and_b32_e32 v50, 0xffff0000, v196
	v_add_f32_e32 v54, 1.0, v54
	v_rcp_f32_e32 v54, v54
	v_pk_mul_f32 v[50:51], v[62:63], v[50:51]
	s_nop 0
	v_add_f32_e32 v50, v72, v50
	v_add_f32_e32 v58, v50, v51
	v_mul_f32_e32 v50, 0xbfb8aa3b, v52
	v_exp_f32_e32 v50, v50
	v_lshlrev_b32_e32 v51, 16, v199
	v_add_f32_e32 v50, 1.0, v50
	v_rcp_f32_e32 v57, v50
	v_lshlrev_b32_e32 v50, 16, v197
	v_pk_mul_f32 v[50:51], v[56:57], v[50:51]
	s_nop 0
	v_add_f32_e32 v50, v71, v50
	v_add_f32_e32 v52, v50, v51
	v_mul_f32_e32 v50, 0xbfb8aa3b, v53
	v_exp_f32_e32 v50, v50
	v_and_b32_e32 v51, 0xffff0000, v199
	v_add_f32_e32 v50, 1.0, v50
	v_rcp_f32_e32 v55, v50
	v_and_b32_e32 v50, 0xffff0000, v197
	v_pk_mul_f32 v[50:51], v[54:55], v[50:51]
	s_nop 0
	v_add_f32_e32 v50, v70, v50
	v_add_f32_e32 v51, v50, v51
	v_cvt_pk_bf16_f32 v50, v64, v58
	v_cvt_pk_bf16_f32 v51, v52, v51
	v_lshlrev_b64 v[52:53], 11, v[66:67]
	v_lshl_add_u64 v[52:53], s[8:9], 0, v[52:53]
	v_lshl_add_u64 v[52:53], v[52:53], 0, v[140:141]
	global_store_dwordx2 v[52:53], v[50:51], off
	v_add_u32_e32 v50, 0x90, v142
	v_ashrrev_i32_e32 v51, 31, v50
	v_lshlrev_b64 v[52:53], 13, v[50:51]
	v_lshl_add_u64 v[52:53], s[6:7], 0, v[52:53]
	v_lshl_add_u64 v[52:53], v[52:53], 0, v[140:141]
	s_nop 0
	s_nop 0
	v_rcp_f32_e32 v54, v47
	v_mul_f32_e32 v47, 0xbfb8aa3b, v48
	v_exp_f32_e32 v47, v47
	s_waitcnt vmcnt(16)
	v_lshlrev_b32_e32 v62, 16, v200
	v_add_f32_e32 v47, 1.0, v47
	v_rcp_f32_e32 v48, v47
	v_mul_f32_e32 v47, 0xbfb8aa3b, v49
	v_exp_f32_e32 v47, v47
	s_waitcnt vmcnt(15)
	v_lshlrev_b32_e32 v63, 16, v202
	v_add_f32_e32 v47, 1.0, v47
	v_rcp_f32_e32 v58, v47
	v_rcp_f32_e32 v47, v42
	s_nop 0
	v_pk_mul_f32 v[46:47], v[46:47], v[62:63]
	s_nop 0
	v_add_f32_e32 v42, 0, v46
	v_add_f32_e32 v47, v42, v47
	v_mul_f32_e32 v42, 0xbfb8aa3b, v43
	v_exp_f32_e32 v42, v42
	v_and_b32_e32 v43, 0xffff0000, v202
	v_add_f32_e32 v42, 1.0, v42
	v_rcp_f32_e32 v55, v42
	v_and_b32_e32 v42, 0xffff0000, v200
	v_pk_mul_f32 v[42:43], v[54:55], v[42:43]
	s_nop 0
	v_add_f32_e32 v42, 0, v42
	v_add_f32_e32 v56, v42, v43
	v_mul_f32_e32 v42, 0xbfb8aa3b, v44
	v_exp_f32_e32 v42, v42
	v_lshlrev_b32_e32 v43, 16, v203
	v_add_co_u32_e32 v44, vcc, s44, v52
	v_add_f32_e32 v42, 1.0, v42
	v_rcp_f32_e32 v49, v42
	v_lshlrev_b32_e32 v42, 16, v201
	v_pk_mul_f32 v[42:43], v[48:49], v[42:43]
	s_nop 0
	v_add_f32_e32 v42, 0, v42
	v_add_f32_e32 v55, v42, v43
	v_mul_f32_e32 v42, 0xbfb8aa3b, v45
	v_exp_f32_e32 v42, v42
	v_and_b32_e32 v43, 0xffff0000, v203
	v_addc_co_u32_e32 v45, vcc, 0, v53, vcc
	v_add_f32_e32 v42, 1.0, v42
	v_rcp_f32_e32 v59, v42
	v_and_b32_e32 v42, 0xffff0000, v201
	v_rcp_f32_e32 v48, v38
	v_rcp_f32_e32 v49, v34
	v_pk_mul_f32 v[42:43], v[58:59], v[42:43]
	v_mul_f32_e32 v38, 0xbfb8aa3b, v39
	v_add_f32_e32 v42, 0, v42
	v_add_f32_e32 v54, v42, v43
	s_nop 0
	v_exp_f32_e32 v38, v38
	s_nop 0
	v_add_f32_e32 v38, 1.0, v38
	v_rcp_f32_e32 v46, v38
	v_mul_f32_e32 v38, 0xbfb8aa3b, v40
	v_exp_f32_e32 v38, v38
	s_waitcnt vmcnt(14)
	v_lshlrev_b32_e32 v52, 16, v204
	v_add_f32_e32 v38, 1.0, v38
	s_waitcnt vmcnt(13)
	v_lshlrev_b32_e32 v53, 16, v206
	v_pk_mul_f32 v[48:49], v[48:49], v[52:53]
	v_rcp_f32_e32 v40, v38
	v_add_f32_e32 v34, v47, v48
	v_add_f32_e32 v48, v34, v49
	v_mul_f32_e32 v34, 0xbfb8aa3b, v35
	v_exp_f32_e32 v34, v34
	v_and_b32_e32 v35, 0xffff0000, v206
	v_mul_f32_e32 v38, 0xbfb8aa3b, v41
	v_exp_f32_e32 v38, v38
	v_add_f32_e32 v34, 1.0, v34
	v_rcp_f32_e32 v47, v34
	v_and_b32_e32 v34, 0xffff0000, v204
	v_add_f32_e32 v38, 1.0, v38
	v_rcp_f32_e32 v38, v38
	v_pk_mul_f32 v[34:35], v[46:47], v[34:35]
	s_nop 0
	v_add_f32_e32 v34, v56, v34
	v_add_f32_e32 v42, v34, v35
	v_mul_f32_e32 v34, 0xbfb8aa3b, v36
	v_exp_f32_e32 v34, v34
	v_lshlrev_b32_e32 v35, 16, v207
	v_add_f32_e32 v34, 1.0, v34
	v_rcp_f32_e32 v41, v34
	v_lshlrev_b32_e32 v34, 16, v205
	v_pk_mul_f32 v[34:35], v[40:41], v[34:35]
	s_nop 0
	v_add_f32_e32 v34, v55, v34
	v_add_f32_e32 v36, v34, v35
	v_mul_f32_e32 v34, 0xbfb8aa3b, v37
	v_exp_f32_e32 v34, v34
	v_and_b32_e32 v35, 0xffff0000, v207
	v_add_f32_e32 v34, 1.0, v34
	v_rcp_f32_e32 v39, v34
	v_and_b32_e32 v34, 0xffff0000, v205
	v_pk_mul_f32 v[34:35], v[38:39], v[34:35]
	s_nop 0
	v_add_f32_e32 v34, v54, v34
	v_add_f32_e32 v35, v34, v35
	v_cvt_pk_bf16_f32 v34, v48, v42
	v_cvt_pk_bf16_f32 v35, v36, v35
	v_lshlrev_b64 v[36:37], 11, v[50:51]
	v_lshl_add_u64 v[36:37], s[8:9], 0, v[36:37]
	v_lshl_add_u64 v[36:37], v[36:37], 0, v[140:141]
	global_store_dwordx2 v[36:37], v[34:35], off
	v_add_u32_e32 v34, 0xa0, v142
	v_ashrrev_i32_e32 v35, 31, v34
	v_lshlrev_b64 v[36:37], 13, v[34:35]
	v_lshl_add_u64 v[36:37], s[6:7], 0, v[36:37]
	v_lshl_add_u64 v[36:37], v[36:37], 0, v[140:141]
	s_nop 0
	s_nop 0
	v_rcp_f32_e32 v38, v31
	v_mul_f32_e32 v31, 0xbfb8aa3b, v32
	v_exp_f32_e32 v31, v31
	s_waitcnt vmcnt(13)
	v_lshlrev_b32_e32 v46, 16, v208
	v_add_f32_e32 v31, 1.0, v31
	v_rcp_f32_e32 v32, v31
	v_mul_f32_e32 v31, 0xbfb8aa3b, v33
	v_exp_f32_e32 v31, v31
	s_waitcnt vmcnt(12)
	v_lshlrev_b32_e32 v47, 16, v228
	v_add_f32_e32 v31, 1.0, v31
	v_rcp_f32_e32 v42, v31
	v_rcp_f32_e32 v31, v26
	s_nop 0
	v_pk_mul_f32 v[30:31], v[30:31], v[46:47]
	s_nop 0
	v_add_f32_e32 v26, 0, v30
	v_add_f32_e32 v31, v26, v31
	v_mul_f32_e32 v26, 0xbfb8aa3b, v27
	v_exp_f32_e32 v26, v26
	v_and_b32_e32 v27, 0xffff0000, v228
	v_add_f32_e32 v26, 1.0, v26
	v_rcp_f32_e32 v39, v26
	v_and_b32_e32 v26, 0xffff0000, v208
	v_pk_mul_f32 v[26:27], v[38:39], v[26:27]
	s_nop 0
	v_add_f32_e32 v26, 0, v26
	v_add_f32_e32 v40, v26, v27
	v_mul_f32_e32 v26, 0xbfb8aa3b, v28
	v_exp_f32_e32 v26, v26
	v_lshlrev_b32_e32 v27, 16, v229
	v_add_co_u32_e32 v28, vcc, s44, v36
	v_add_f32_e32 v26, 1.0, v26
	v_rcp_f32_e32 v33, v26
	v_lshlrev_b32_e32 v26, 16, v209
	v_pk_mul_f32 v[26:27], v[32:33], v[26:27]
	s_nop 0
	v_add_f32_e32 v26, 0, v26
	v_add_f32_e32 v39, v26, v27
	v_mul_f32_e32 v26, 0xbfb8aa3b, v29
	v_exp_f32_e32 v26, v26
	v_and_b32_e32 v27, 0xffff0000, v229
	v_addc_co_u32_e32 v29, vcc, 0, v37, vcc
	v_add_f32_e32 v26, 1.0, v26
	v_rcp_f32_e32 v43, v26
	v_and_b32_e32 v26, 0xffff0000, v209
	v_rcp_f32_e32 v32, v22
	v_rcp_f32_e32 v33, v18
	v_pk_mul_f32 v[26:27], v[42:43], v[26:27]
	v_mul_f32_e32 v22, 0xbfb8aa3b, v23
	v_add_f32_e32 v26, 0, v26
	v_add_f32_e32 v38, v26, v27
	s_nop 0
	v_exp_f32_e32 v22, v22
	s_nop 0
	v_add_f32_e32 v22, 1.0, v22
	v_rcp_f32_e32 v30, v22
	v_mul_f32_e32 v22, 0xbfb8aa3b, v24
	v_exp_f32_e32 v22, v22
	s_waitcnt vmcnt(11)
	v_lshlrev_b32_e32 v36, 16, v230
	v_add_f32_e32 v22, 1.0, v22
	s_waitcnt vmcnt(10)
	v_lshlrev_b32_e32 v37, 16, v232
	v_pk_mul_f32 v[32:33], v[32:33], v[36:37]
	v_rcp_f32_e32 v24, v22
	v_add_f32_e32 v18, v31, v32
	v_add_f32_e32 v32, v18, v33
	v_mul_f32_e32 v18, 0xbfb8aa3b, v19
	v_exp_f32_e32 v18, v18
	v_and_b32_e32 v19, 0xffff0000, v232
	v_mul_f32_e32 v22, 0xbfb8aa3b, v25
	v_exp_f32_e32 v22, v22
	v_add_f32_e32 v18, 1.0, v18
	v_rcp_f32_e32 v31, v18
	v_and_b32_e32 v18, 0xffff0000, v230
	v_add_f32_e32 v22, 1.0, v22
	v_rcp_f32_e32 v22, v22
	v_pk_mul_f32 v[18:19], v[30:31], v[18:19]
	s_nop 0
	v_add_f32_e32 v18, v40, v18
	v_add_f32_e32 v26, v18, v19
	v_mul_f32_e32 v18, 0xbfb8aa3b, v20
	v_exp_f32_e32 v18, v18
	v_lshlrev_b32_e32 v19, 16, v233
	v_add_f32_e32 v18, 1.0, v18
	v_rcp_f32_e32 v25, v18
	v_lshlrev_b32_e32 v18, 16, v231
	v_pk_mul_f32 v[18:19], v[24:25], v[18:19]
	s_nop 0
	v_add_f32_e32 v18, v39, v18
	v_add_f32_e32 v20, v18, v19
	v_mul_f32_e32 v18, 0xbfb8aa3b, v21
	v_exp_f32_e32 v18, v18
	v_and_b32_e32 v19, 0xffff0000, v233
	v_add_f32_e32 v18, 1.0, v18
	v_rcp_f32_e32 v23, v18
	v_and_b32_e32 v18, 0xffff0000, v231
	v_pk_mul_f32 v[18:19], v[22:23], v[18:19]
	s_nop 0
	v_add_f32_e32 v18, v38, v18
	v_add_f32_e32 v19, v18, v19
	v_cvt_pk_bf16_f32 v18, v32, v26
	v_cvt_pk_bf16_f32 v19, v20, v19
	v_lshlrev_b64 v[20:21], 11, v[34:35]
	v_lshl_add_u64 v[20:21], s[8:9], 0, v[20:21]
	v_lshl_add_u64 v[20:21], v[20:21], 0, v[140:141]
	global_store_dwordx2 v[20:21], v[18:19], off
	v_add_u32_e32 v18, 0xb0, v142
	v_ashrrev_i32_e32 v19, 31, v18
	v_lshlrev_b64 v[20:21], 13, v[18:19]
	v_lshl_add_u64 v[20:21], s[6:7], 0, v[20:21]
	v_lshl_add_u64 v[20:21], v[20:21], 0, v[140:141]
	s_nop 0
	s_nop 0
	v_rcp_f32_e32 v22, v15
	v_mul_f32_e32 v15, 0xbfb8aa3b, v16
	v_exp_f32_e32 v15, v15
	s_waitcnt vmcnt(10)
	v_lshlrev_b32_e32 v30, 16, v234
	v_add_f32_e32 v15, 1.0, v15
	v_rcp_f32_e32 v16, v15
	v_mul_f32_e32 v15, 0xbfb8aa3b, v17
	v_exp_f32_e32 v15, v15
	s_waitcnt vmcnt(9)
	v_lshlrev_b32_e32 v31, 16, v236
	v_add_f32_e32 v15, 1.0, v15
	v_rcp_f32_e32 v26, v15
	v_rcp_f32_e32 v15, v10
	s_nop 0
	v_pk_mul_f32 v[14:15], v[14:15], v[30:31]
	s_nop 0
	v_add_f32_e32 v10, 0, v14
	v_add_f32_e32 v15, v10, v15
	v_mul_f32_e32 v10, 0xbfb8aa3b, v11
	v_exp_f32_e32 v10, v10
	v_and_b32_e32 v11, 0xffff0000, v236
	v_add_f32_e32 v10, 1.0, v10
	v_rcp_f32_e32 v23, v10
	v_and_b32_e32 v10, 0xffff0000, v234
	v_pk_mul_f32 v[10:11], v[22:23], v[10:11]
	s_nop 0
	v_add_f32_e32 v10, 0, v10
	v_add_f32_e32 v24, v10, v11
	v_mul_f32_e32 v10, 0xbfb8aa3b, v12
	v_exp_f32_e32 v10, v10
	v_lshlrev_b32_e32 v11, 16, v237
	v_add_co_u32_e32 v12, vcc, s44, v20
	v_add_f32_e32 v10, 1.0, v10
	v_rcp_f32_e32 v17, v10
	v_lshlrev_b32_e32 v10, 16, v235
	v_pk_mul_f32 v[10:11], v[16:17], v[10:11]
	s_nop 0
	v_add_f32_e32 v10, 0, v10
	v_add_f32_e32 v23, v10, v11
	v_mul_f32_e32 v10, 0xbfb8aa3b, v13
	v_exp_f32_e32 v10, v10
	v_and_b32_e32 v11, 0xffff0000, v237
	v_addc_co_u32_e32 v13, vcc, 0, v21, vcc
	v_add_f32_e32 v10, 1.0, v10
	v_rcp_f32_e32 v27, v10
	v_and_b32_e32 v10, 0xffff0000, v235
	v_rcp_f32_e32 v16, v6
	v_rcp_f32_e32 v17, v2
	v_pk_mul_f32 v[10:11], v[26:27], v[10:11]
	v_mul_f32_e32 v6, 0xbfb8aa3b, v7
	v_add_f32_e32 v10, 0, v10
	v_add_f32_e32 v22, v10, v11
	s_nop 0
	v_exp_f32_e32 v6, v6
	s_nop 0
	s_andn2_b64 vcc, exec, s[4:5]
	v_add_f32_e32 v6, 1.0, v6
	v_rcp_f32_e32 v14, v6
	v_mul_f32_e32 v6, 0xbfb8aa3b, v8
	v_exp_f32_e32 v6, v6
	s_waitcnt vmcnt(8)
	v_lshlrev_b32_e32 v20, 16, v238
	v_add_f32_e32 v6, 1.0, v6
	s_waitcnt vmcnt(7)
	v_lshlrev_b32_e32 v21, 16, v240
	v_pk_mul_f32 v[16:17], v[16:17], v[20:21]
	v_rcp_f32_e32 v8, v6
	v_add_f32_e32 v2, v15, v16
	v_add_f32_e32 v16, v2, v17
	v_mul_f32_e32 v2, 0xbfb8aa3b, v3
	v_exp_f32_e32 v2, v2
	v_and_b32_e32 v3, 0xffff0000, v240
	v_mul_f32_e32 v6, 0xbfb8aa3b, v9
	v_exp_f32_e32 v6, v6
	v_add_f32_e32 v2, 1.0, v2
	v_rcp_f32_e32 v15, v2
	v_and_b32_e32 v2, 0xffff0000, v238
	v_add_f32_e32 v6, 1.0, v6
	v_rcp_f32_e32 v6, v6
	v_pk_mul_f32 v[2:3], v[14:15], v[2:3]
	s_nop 0
	v_add_f32_e32 v2, v24, v2
	v_add_f32_e32 v10, v2, v3
	v_mul_f32_e32 v2, 0xbfb8aa3b, v4
	v_exp_f32_e32 v2, v2
	v_lshlrev_b32_e32 v3, 16, v241
	v_add_f32_e32 v2, 1.0, v2
	v_rcp_f32_e32 v9, v2
	v_lshlrev_b32_e32 v2, 16, v239
	v_pk_mul_f32 v[2:3], v[8:9], v[2:3]
	s_nop 0
	v_add_f32_e32 v2, v23, v2
	v_add_f32_e32 v4, v2, v3
	v_mul_f32_e32 v2, 0xbfb8aa3b, v5
	v_exp_f32_e32 v2, v2
	v_and_b32_e32 v3, 0xffff0000, v241
	v_add_f32_e32 v2, 1.0, v2
	v_rcp_f32_e32 v7, v2
	v_and_b32_e32 v2, 0xffff0000, v239
	v_pk_mul_f32 v[2:3], v[6:7], v[2:3]
	s_nop 0
	v_add_f32_e32 v2, v22, v2
	v_add_f32_e32 v3, v2, v3
	v_cvt_pk_bf16_f32 v2, v16, v10
	v_cvt_pk_bf16_f32 v3, v4, v3
	v_lshlrev_b64 v[4:5], 11, v[18:19]
	v_lshl_add_u64 v[4:5], s[8:9], 0, v[4:5]
	v_lshl_add_u64 v[4:5], v[4:5], 0, v[140:141]
	global_store_dwordx2 v[4:5], v[2:3], off
	s_cbranch_vccnz .LBB0_1599
	s_andn2_b64 vcc, exec, s[0:1]
	s_cbranch_vccnz .LBB0_1598
	s_barrier
	s_branch .LBB0_1598
